# attention: LDS-DMA destinations as literal offsets from the ring base; V offset SGPR only in the PV-only block
# speedup vs baseline: 1.0157x; 1.0035x over previous
.LBB0_174:
	s_cmp_ge_u32 s23, s19
	s_cbranch_scc1 .Lslow_u1e
.LBB0_185:
	ds_read_b128 v[126:129], v244 offset:16384
	s_waitcnt lgkmcnt(1)
	v_mfma_f32_32x32x16_bf16 v[82:97], v[98:101], v[146:149], v[66:81]
	ds_read_b128 v[122:125], v240 offset:24576
	v_mfma_f32_32x32x16_bf16 v[98:113], v[114:117], v[146:149], v[66:81]
	ds_read_b128 v[114:117], v241 offset:16384
	v_mfma_f32_32x32x16_bf16 v[82:97], v[118:121], v[150:153], v[82:97]
	ds_read_b128 v[118:121], v241 offset:24576
	s_waitcnt lgkmcnt(0)
	v_mfma_f32_32x32x16_bf16 v[98:113], v[122:125], v[150:153], v[98:113]
	ds_read_b128 v[122:125], v243 offset:16384
	v_mfma_f32_32x32x16_bf16 v[82:97], v[114:117], v[154:157], v[82:97]
	ds_read_b128 v[114:117], v243 offset:24576
	v_mfma_f32_32x32x16_bf16 v[98:113], v[118:121], v[154:157], v[98:113]
	s_waitcnt lgkmcnt(0)
	v_mfma_f32_32x32x16_bf16 v[82:97], v[122:125], v[158:161], v[82:97]
	v_mfma_f32_32x32x16_bf16 v[98:113], v[114:117], v[158:161], v[98:113]
	s_nop 0
	ds_read_b128 v[122:125], v244 offset:20480
	ds_read_b128 v[118:121], v244 offset:24576
	ds_read_b128 v[114:117], v244 offset:28672
	s_add_i32 s22, s21, 64
	s_cmp_le_u32 s22, s20
	s_cbranch_scc0 .Lnear_u1e
.LBB0_188:
	v_mfma_f32_32x32x16_bf16 v[34:49], v[126:129], v[162:165], v[34:49]
	ds_read_b128 v[126:129], v245 offset:16384
	s_nop 0
	v_exp_f32_e32 v130, v82
	v_exp_f32_e32 v131, v83
	v_add_f32_e32 v132, v1, v130
	v_add_f32_e32 v133, v1, v131
	v_cvt_pk_bf16_f32 v166, v130, v131
	s_waitcnt lgkmcnt(3)
	v_mfma_f32_32x32x16_bf16 v[50:65], v[122:125], v[162:165], v[50:65]
	ds_read_b128 v[122:125], v245 offset:20480
	v_exp_f32_e32 v134, v84
	v_exp_f32_e32 v135, v85
	s_add_i32 s22, s23, 2
	v_add_f32_e32 v130, v132, v134
	v_add_f32_e32 v131, v133, v135
	v_cvt_pk_bf16_f32 v167, v134, v135
	s_mov_b32 m0, s11
	s_cmp_ge_u32 s22, s17
	s_cbranch_scc1 .LBB0_190
	global_load_lds_dwordx4 v214, s[80:81]
	s_add_i32 m0, s11, 0x2000
	s_nop 0
	global_load_lds_dwordx4 v214, s[62:63]

.LBB0_192:
	s_waitcnt lgkmcnt(2)
	v_mfma_f32_32x32x16_bf16 v[18:33], v[118:121], v[170:173], v[18:33]
	ds_read_b128 v[118:121], v246 offset:24576
	v_exp_f32_e32 v133, v94
	v_exp_f32_e32 v134, v95
	v_add_f32_e32 v131, v131, v133
	v_add_f32_e32 v132, v132, v134
	v_cvt_pk_bf16_f32 v176, v133, v134
	v_mfma_f32_32x32x16_bf16 v[2:17], v[114:117], v[170:173], v[2:17]
	ds_read_b128 v[114:117], v246 offset:28672
	v_exp_f32_e32 v130, v96
	v_exp_f32_e32 v133, v97
	v_add_f32_e32 v131, v131, v130
	v_add_f32_e32 v132, v132, v133
	v_cvt_pk_bf16_f32 v177, v130, v133
	s_waitcnt lgkmcnt(2)
	v_mfma_f32_32x32x16_bf16 v[34:49], v[126:129], v[178:181], v[34:49]
	ds_read_b128 v[126:129], v247 offset:16384
	v_exp_f32_e32 v133, v98
	v_exp_f32_e32 v134, v99
	v_add_f32_e32 v131, v131, v133
	v_add_f32_e32 v132, v132, v134
	v_cvt_pk_bf16_f32 v182, v133, v134
	v_mfma_f32_32x32x16_bf16 v[50:65], v[122:125], v[178:181], v[50:65]
	v_exp_f32_e32 v133, v100
	v_exp_f32_e32 v134, v101
	ds_read_b128 v[122:125], v247 offset:20480
	v_add_f32_e32 v131, v131, v133
	v_add_f32_e32 v132, v132, v134
	v_cvt_pk_bf16_f32 v183, v133, v134
	s_add_i32 m0, s11, 0x14000
	s_cmp_eq_u64 s[88:89], 0
	s_cbranch_scc1 .LBB0_194
	global_load_lds_dwordx4 v216, s[96:97]
	s_add_i32 m0, s11, 0x16000
	s_nop 0
	global_load_lds_dwordx4 v216, s[58:59]

.LBB0_214:
	s_add_i32 s40, s23, 1
	s_cmp_ge_u32 s40, s19
	s_cbranch_scc1 .Lslow_u1o
.LBB0_225:
	ds_read_b128 v[126:129], v244 offset:32768
	s_waitcnt lgkmcnt(1)
	v_mfma_f32_32x32x16_bf16 v[82:97], v[98:101], v[146:149], v[66:81]
	ds_read_b128 v[122:125], v240 offset:40960
	v_mfma_f32_32x32x16_bf16 v[98:113], v[114:117], v[146:149], v[66:81]
	ds_read_b128 v[114:117], v241 offset:32768
	v_mfma_f32_32x32x16_bf16 v[82:97], v[118:121], v[150:153], v[82:97]
	ds_read_b128 v[118:121], v241 offset:40960
	s_waitcnt lgkmcnt(0)
	v_mfma_f32_32x32x16_bf16 v[98:113], v[122:125], v[150:153], v[98:113]
	ds_read_b128 v[122:125], v243 offset:32768
	v_mfma_f32_32x32x16_bf16 v[82:97], v[114:117], v[154:157], v[82:97]
	ds_read_b128 v[114:117], v243 offset:40960
	v_mfma_f32_32x32x16_bf16 v[98:113], v[118:121], v[154:157], v[98:113]
	s_waitcnt lgkmcnt(0)
	v_mfma_f32_32x32x16_bf16 v[82:97], v[122:125], v[158:161], v[82:97]
	v_mfma_f32_32x32x16_bf16 v[98:113], v[114:117], v[158:161], v[98:113]
	s_nop 0
	ds_read_b128 v[122:125], v244 offset:36864
	ds_read_b128 v[118:121], v244 offset:40960
	ds_read_b128 v[114:117], v244 offset:45056
	s_add_i32 s26, s21, 0x80
	s_cmp_le_u32 s26, s20
	s_cbranch_scc0 .Lnear_u1o
.LBB0_228:
	v_mfma_f32_32x32x16_bf16 v[34:49], v[126:129], v[166:169], v[34:49]
	ds_read_b128 v[126:129], v245 offset:32768
	s_nop 0
	v_exp_f32_e32 v130, v82
	v_exp_f32_e32 v131, v83
	v_add_f32_e32 v132, v1, v130
	v_add_f32_e32 v133, v1, v131
	v_cvt_pk_bf16_f32 v162, v130, v131
	s_waitcnt lgkmcnt(3)
	v_mfma_f32_32x32x16_bf16 v[50:65], v[122:125], v[166:169], v[50:65]
	ds_read_b128 v[122:125], v245 offset:36864
	v_exp_f32_e32 v130, v84
	v_exp_f32_e32 v131, v85
	s_add_i32 s23, s23, 3
	v_add_f32_e32 v132, v132, v130
	v_add_f32_e32 v133, v133, v131
	v_cvt_pk_bf16_f32 v163, v130, v131
	s_add_i32 m0, s11, 0x4000
	s_cmp_gt_u32 s23, s16
	s_cbranch_scc1 .LBB0_230
	global_load_lds_dwordx4 v214, s[50:51]
	s_add_i32 m0, s11, 0x6000
	s_nop 0
	global_load_lds_dwordx4 v214, s[4:5]

.LBB0_232:
	s_waitcnt lgkmcnt(2)
	v_mfma_f32_32x32x16_bf16 v[18:33], v[118:121], v[174:177], v[18:33]
	ds_read_b128 v[118:121], v246 offset:40960
	v_exp_f32_e32 v130, v94
	v_exp_f32_e32 v131, v95
	v_add_f32_e32 v133, v133, v130
	v_add_f32_e32 v134, v134, v131
	v_cvt_pk_bf16_f32 v172, v130, v131
	v_mfma_f32_32x32x16_bf16 v[2:17], v[114:117], v[174:177], v[2:17]
	ds_read_b128 v[114:117], v246 offset:45056
	v_exp_f32_e32 v130, v96
	v_exp_f32_e32 v131, v97
	v_add_f32_e32 v133, v133, v130
	v_add_f32_e32 v134, v134, v131
	v_cvt_pk_bf16_f32 v173, v130, v131
	s_waitcnt lgkmcnt(2)
	v_mfma_f32_32x32x16_bf16 v[34:49], v[126:129], v[182:185], v[34:49]
	ds_read_b128 v[126:129], v247 offset:32768
	v_exp_f32_e32 v130, v98
	v_exp_f32_e32 v131, v99
	v_add_f32_e32 v133, v133, v130
	v_add_f32_e32 v134, v134, v131
	v_cvt_pk_bf16_f32 v178, v130, v131
	v_mfma_f32_32x32x16_bf16 v[50:65], v[122:125], v[182:185], v[50:65]
	v_exp_f32_e32 v130, v100
	v_exp_f32_e32 v131, v101
	ds_read_b128 v[122:125], v247 offset:36864
	v_add_f32_e32 v133, v133, v130
	v_add_f32_e32 v134, v134, v131
	v_cvt_pk_bf16_f32 v179, v130, v131
	s_add_i32 m0, s11, 0xc000
	s_cmp_eq_u64 s[88:89], 0
	s_cbranch_scc1 .LBB0_234
	global_load_lds_dwordx4 v216, s[0:1]
	s_add_i32 m0, s11, 0xe000
	s_nop 0
	global_load_lds_dwordx4 v216, s[52:53]

.Lpvo_u1e:
	s_mov_b32 s54, 0xffff8000
	v_add_u32_e32 v249, s54, v244
	v_add_u32_e32 v212, s54, v245
	s_mov_b64 s[26:27], -1
	ds_read_b128 v[98:101], v249 offset:49152
	ds_read_b128 v[114:117], v249 offset:53248
	ds_read_b128 v[130:133], v249 offset:57344
	ds_read_b128 v[194:197], v249 offset:61440
	s_waitcnt lgkmcnt(0)
	v_mfma_f32_32x32x16_bf16 v[82:97], v[98:101], v[162:165], v[34:49]
	ds_read_b128 v[206:209], v212 offset:49152
	v_mfma_f32_32x32x16_bf16 v[98:113], v[114:117], v[162:165], v[50:65]
	ds_read_b128 v[198:201], v212 offset:53248
	s_add_i32 s22, s23, 2
	s_cmp_lt_u32 s22, s17
	s_cselect_b64 s[26:27], -1, 0
	s_cmp_ge_u32 s22, s17
	s_cbranch_scc1 .LBB0_178
	s_mov_b32 s40, 0x0
	s_add_i32 m0, s11, s40
	s_nop 0
	global_load_lds_dwordx4 v214, s[80:81]

.Lpvo_u1o:
	s_mov_b32 s54, 0xffffc000
	v_add_u32_e32 v249, s54, v244
	v_add_u32_e32 v212, s54, v245
	s_mov_b64 s[26:27], -1
	ds_read_b128 v[98:101], v249 offset:49152
	ds_read_b128 v[114:117], v249 offset:53248
	ds_read_b128 v[130:133], v249 offset:57344
	ds_read_b128 v[194:197], v249 offset:61440
	s_waitcnt lgkmcnt(0)
	v_mfma_f32_32x32x16_bf16 v[82:97], v[98:101], v[166:169], v[34:49]
	ds_read_b128 v[206:209], v212 offset:49152
	v_mfma_f32_32x32x16_bf16 v[98:113], v[114:117], v[166:169], v[50:65]
	ds_read_b128 v[198:201], v212 offset:53248
	s_add_i32 s40, s23, 3
	s_cmp_le_u32 s40, s16
	s_cselect_b64 s[26:27], -1, 0
	s_cmp_gt_u32 s40, s16
	s_cbranch_scc1 .LBB0_218
	s_mov_b32 s40, 0x4000
	s_add_i32 m0, s11, s40
	s_nop 0
	global_load_lds_dwordx4 v214, s[50:51]

.Lr1u1_LBB0_185:
	ds_read_b128 v[126:129], v244 offset:49152
	s_waitcnt lgkmcnt(1)
	v_mfma_f32_32x32x16_bf16 v[82:97], v[98:101], v[146:149], v[66:81]
	ds_read_b128 v[122:125], v240 offset:8192
	v_mfma_f32_32x32x16_bf16 v[98:113], v[114:117], v[146:149], v[66:81]
	ds_read_b128 v[114:117], v241
	v_mfma_f32_32x32x16_bf16 v[82:97], v[118:121], v[150:153], v[82:97]
	ds_read_b128 v[118:121], v241 offset:8192
	s_waitcnt lgkmcnt(0)
	v_mfma_f32_32x32x16_bf16 v[98:113], v[122:125], v[150:153], v[98:113]
	ds_read_b128 v[122:125], v243
	v_mfma_f32_32x32x16_bf16 v[82:97], v[114:117], v[154:157], v[82:97]
	ds_read_b128 v[114:117], v243 offset:8192
	v_mfma_f32_32x32x16_bf16 v[98:113], v[118:121], v[154:157], v[98:113]
	s_waitcnt lgkmcnt(0)
	v_mfma_f32_32x32x16_bf16 v[82:97], v[122:125], v[158:161], v[82:97]
	v_mfma_f32_32x32x16_bf16 v[98:113], v[114:117], v[158:161], v[98:113]
	s_nop 0
	ds_read_b128 v[122:125], v244 offset:53248
	ds_read_b128 v[118:121], v244 offset:57344
	ds_read_b128 v[114:117], v244 offset:61440
	s_add_i32 s22, s21, 64
	s_cmp_le_u32 s22, s20
	s_cbranch_scc0 .Lr1u1_Lnear_u1e
.Lr1u1_LBB0_188:
	v_mfma_f32_32x32x16_bf16 v[34:49], v[126:129], v[162:165], v[34:49]
	ds_read_b128 v[126:129], v245 offset:49152
	s_nop 0
	v_exp_f32_e32 v130, v82
	v_exp_f32_e32 v131, v83
	v_add_f32_e32 v132, v1, v130
	v_add_f32_e32 v133, v1, v131
	v_cvt_pk_bf16_f32 v166, v130, v131
	s_waitcnt lgkmcnt(3)
	v_mfma_f32_32x32x16_bf16 v[50:65], v[122:125], v[162:165], v[50:65]
	ds_read_b128 v[122:125], v245 offset:53248
	v_exp_f32_e32 v134, v84
	v_exp_f32_e32 v135, v85
	s_add_i32 s22, s23, 2
	v_add_f32_e32 v130, v132, v134
	v_add_f32_e32 v131, v133, v135
	v_cvt_pk_bf16_f32 v167, v134, v135
	s_add_i32 m0, s11, 0x8000
	s_cmp_ge_u32 s22, s17
	s_cbranch_scc1 .Lr1u1_LBB0_190
	global_load_lds_dwordx4 v214, s[80:81]
	s_add_i32 m0, s11, 0xa000
	s_nop 0
	global_load_lds_dwordx4 v214, s[62:63]

.Lr1u1_LBB0_192:
	s_waitcnt lgkmcnt(2)
	v_mfma_f32_32x32x16_bf16 v[18:33], v[118:121], v[170:173], v[18:33]
	ds_read_b128 v[118:121], v246 offset:57344
	v_exp_f32_e32 v133, v94
	v_exp_f32_e32 v134, v95
	v_add_f32_e32 v131, v131, v133
	v_add_f32_e32 v132, v132, v134
	v_cvt_pk_bf16_f32 v176, v133, v134
	v_mfma_f32_32x32x16_bf16 v[2:17], v[114:117], v[170:173], v[2:17]
	ds_read_b128 v[114:117], v246 offset:61440
	v_exp_f32_e32 v130, v96
	v_exp_f32_e32 v133, v97
	v_add_f32_e32 v131, v131, v130
	v_add_f32_e32 v132, v132, v133
	v_cvt_pk_bf16_f32 v177, v130, v133
	s_waitcnt lgkmcnt(2)
	v_mfma_f32_32x32x16_bf16 v[34:49], v[126:129], v[178:181], v[34:49]
	ds_read_b128 v[126:129], v247 offset:49152
	v_exp_f32_e32 v133, v98
	v_exp_f32_e32 v134, v99
	v_add_f32_e32 v131, v131, v133
	v_add_f32_e32 v132, v132, v134
	v_cvt_pk_bf16_f32 v182, v133, v134
	v_mfma_f32_32x32x16_bf16 v[50:65], v[122:125], v[178:181], v[50:65]
	v_exp_f32_e32 v133, v100
	v_exp_f32_e32 v134, v101
	ds_read_b128 v[122:125], v247 offset:53248
	v_add_f32_e32 v131, v131, v133
	v_add_f32_e32 v132, v132, v134
	v_cvt_pk_bf16_f32 v183, v133, v134
	s_add_i32 m0, s11, 0x10000
	s_cmp_eq_u64 s[88:89], 0
	s_cbranch_scc1 .Lr1u1_LBB0_194
	global_load_lds_dwordx4 v216, s[96:97]
	s_add_i32 m0, s11, 0x12000
	s_nop 0
	global_load_lds_dwordx4 v216, s[58:59]

.Lr1u1_LBB0_225:
	ds_read_b128 v[126:129], v244 offset:16384
	s_waitcnt lgkmcnt(1)
	v_mfma_f32_32x32x16_bf16 v[82:97], v[98:101], v[146:149], v[66:81]
	ds_read_b128 v[122:125], v240 offset:24576
	v_mfma_f32_32x32x16_bf16 v[98:113], v[114:117], v[146:149], v[66:81]
	ds_read_b128 v[114:117], v241 offset:16384
	v_mfma_f32_32x32x16_bf16 v[82:97], v[118:121], v[150:153], v[82:97]
	ds_read_b128 v[118:121], v241 offset:24576
	s_waitcnt lgkmcnt(0)
	v_mfma_f32_32x32x16_bf16 v[98:113], v[122:125], v[150:153], v[98:113]
	ds_read_b128 v[122:125], v243 offset:16384
	v_mfma_f32_32x32x16_bf16 v[82:97], v[114:117], v[154:157], v[82:97]
	ds_read_b128 v[114:117], v243 offset:24576
	v_mfma_f32_32x32x16_bf16 v[98:113], v[118:121], v[154:157], v[98:113]
	s_waitcnt lgkmcnt(0)
	v_mfma_f32_32x32x16_bf16 v[82:97], v[122:125], v[158:161], v[82:97]
	v_mfma_f32_32x32x16_bf16 v[98:113], v[114:117], v[158:161], v[98:113]
	s_nop 0
	ds_read_b128 v[122:125], v244 offset:20480
	ds_read_b128 v[118:121], v244 offset:24576
	ds_read_b128 v[114:117], v244 offset:28672
	s_add_i32 s26, s21, 0x80
	s_cmp_le_u32 s26, s20
	s_cbranch_scc0 .Lr1u1_Lnear_u1o
.Lr1u1_LBB0_228:
	v_mfma_f32_32x32x16_bf16 v[34:49], v[126:129], v[166:169], v[34:49]
	ds_read_b128 v[126:129], v245 offset:16384
	s_nop 0
	v_exp_f32_e32 v130, v82
	v_exp_f32_e32 v131, v83
	v_add_f32_e32 v132, v1, v130
	v_add_f32_e32 v133, v1, v131
	v_cvt_pk_bf16_f32 v162, v130, v131
	s_waitcnt lgkmcnt(3)
	v_mfma_f32_32x32x16_bf16 v[50:65], v[122:125], v[166:169], v[50:65]
	ds_read_b128 v[122:125], v245 offset:20480
	v_exp_f32_e32 v130, v84
	v_exp_f32_e32 v131, v85
	s_add_i32 s23, s23, 3
	v_add_f32_e32 v132, v132, v130
	v_add_f32_e32 v133, v133, v131
	v_cvt_pk_bf16_f32 v163, v130, v131
	s_mov_b32 m0, s11
	s_cmp_gt_u32 s23, s16
	s_cbranch_scc1 .Lr1u1_LBB0_230
	global_load_lds_dwordx4 v214, s[50:51]
	s_add_i32 m0, s11, 0x2000
	s_nop 0
	global_load_lds_dwordx4 v214, s[4:5]

.Lr1u1_LBB0_232:
	s_waitcnt lgkmcnt(2)
	v_mfma_f32_32x32x16_bf16 v[18:33], v[118:121], v[174:177], v[18:33]
	ds_read_b128 v[118:121], v246 offset:24576
	v_exp_f32_e32 v130, v94
	v_exp_f32_e32 v131, v95
	v_add_f32_e32 v133, v133, v130
	v_add_f32_e32 v134, v134, v131
	v_cvt_pk_bf16_f32 v172, v130, v131
	v_mfma_f32_32x32x16_bf16 v[2:17], v[114:117], v[174:177], v[2:17]
	ds_read_b128 v[114:117], v246 offset:28672
	v_exp_f32_e32 v130, v96
	v_exp_f32_e32 v131, v97
	v_add_f32_e32 v133, v133, v130
	v_add_f32_e32 v134, v134, v131
	v_cvt_pk_bf16_f32 v173, v130, v131
	s_waitcnt lgkmcnt(2)
	v_mfma_f32_32x32x16_bf16 v[34:49], v[126:129], v[182:185], v[34:49]
	ds_read_b128 v[126:129], v247 offset:16384
	v_exp_f32_e32 v130, v98
	v_exp_f32_e32 v131, v99
	v_add_f32_e32 v133, v133, v130
	v_add_f32_e32 v134, v134, v131
	v_cvt_pk_bf16_f32 v178, v130, v131
	v_mfma_f32_32x32x16_bf16 v[50:65], v[122:125], v[182:185], v[50:65]
	v_exp_f32_e32 v130, v100
	v_exp_f32_e32 v131, v101
	ds_read_b128 v[122:125], v247 offset:20480
	v_add_f32_e32 v133, v133, v130
	v_add_f32_e32 v134, v134, v131
	v_cvt_pk_bf16_f32 v179, v130, v131
	s_add_i32 m0, s11, 0x14000
	s_cmp_eq_u64 s[88:89], 0
	s_cbranch_scc1 .Lr1u1_LBB0_234
	global_load_lds_dwordx4 v216, s[0:1]
	s_add_i32 m0, s11, 0x16000
	s_nop 0
	global_load_lds_dwordx4 v216, s[52:53]

.Lr1u1_Lpvo_u1e:
	s_mov_b32 s54, 0x0
	v_add_u32_e32 v249, s54, v244
	v_add_u32_e32 v212, s54, v245
	s_mov_b64 s[26:27], -1
	ds_read_b128 v[98:101], v249 offset:49152
	ds_read_b128 v[114:117], v249 offset:53248
	ds_read_b128 v[130:133], v249 offset:57344
	ds_read_b128 v[194:197], v249 offset:61440
	s_waitcnt lgkmcnt(0)
	v_mfma_f32_32x32x16_bf16 v[82:97], v[98:101], v[162:165], v[34:49]
	ds_read_b128 v[206:209], v212 offset:49152
	v_mfma_f32_32x32x16_bf16 v[98:113], v[114:117], v[162:165], v[50:65]
	ds_read_b128 v[198:201], v212 offset:53248
	s_add_i32 s22, s23, 2
	s_cmp_lt_u32 s22, s17
	s_cselect_b64 s[26:27], -1, 0
	s_cmp_ge_u32 s22, s17
	s_cbranch_scc1 .Lr1u1_LBB0_178
	s_mov_b32 s40, 0x8000
	s_add_i32 m0, s11, s40
	s_nop 0
	global_load_lds_dwordx4 v214, s[80:81]

.Lr1u1_Lpvo_u1o:
	s_mov_b32 s54, 0xffff8000
	v_add_u32_e32 v249, s54, v244
	v_add_u32_e32 v212, s54, v245
	s_mov_b64 s[26:27], -1
	ds_read_b128 v[98:101], v249 offset:49152
	ds_read_b128 v[114:117], v249 offset:53248
	ds_read_b128 v[130:133], v249 offset:57344
	ds_read_b128 v[194:197], v249 offset:61440
	s_waitcnt lgkmcnt(0)
	v_mfma_f32_32x32x16_bf16 v[82:97], v[98:101], v[166:169], v[34:49]
	ds_read_b128 v[206:209], v212 offset:49152
	v_mfma_f32_32x32x16_bf16 v[98:113], v[114:117], v[166:169], v[50:65]
	ds_read_b128 v[198:201], v212 offset:53248
	s_add_i32 s40, s23, 3
	s_cmp_le_u32 s40, s16
	s_cselect_b64 s[26:27], -1, 0
	s_cmp_gt_u32 s40, s16
	s_cbranch_scc1 .Lr1u1_LBB0_218
	s_mov_b32 s40, 0x0
	s_add_i32 m0, s11, s40
	s_nop 0
	global_load_lds_dwordx4 v214, s[50:51]

.Lr2u1_LBB0_185:
	ds_read_b128 v[126:129], v244 offset:32768
	s_waitcnt lgkmcnt(1)
	v_mfma_f32_32x32x16_bf16 v[82:97], v[98:101], v[146:149], v[66:81]
	ds_read_b128 v[122:125], v240 offset:40960
	v_mfma_f32_32x32x16_bf16 v[98:113], v[114:117], v[146:149], v[66:81]
	ds_read_b128 v[114:117], v241 offset:32768
	v_mfma_f32_32x32x16_bf16 v[82:97], v[118:121], v[150:153], v[82:97]
	ds_read_b128 v[118:121], v241 offset:40960
	s_waitcnt lgkmcnt(0)
	v_mfma_f32_32x32x16_bf16 v[98:113], v[122:125], v[150:153], v[98:113]
	ds_read_b128 v[122:125], v243 offset:32768
	v_mfma_f32_32x32x16_bf16 v[82:97], v[114:117], v[154:157], v[82:97]
	ds_read_b128 v[114:117], v243 offset:40960
	v_mfma_f32_32x32x16_bf16 v[98:113], v[118:121], v[154:157], v[98:113]
	s_waitcnt lgkmcnt(0)
	v_mfma_f32_32x32x16_bf16 v[82:97], v[122:125], v[158:161], v[82:97]
	v_mfma_f32_32x32x16_bf16 v[98:113], v[114:117], v[158:161], v[98:113]
	s_nop 0
	ds_read_b128 v[122:125], v244 offset:36864
	ds_read_b128 v[118:121], v244 offset:40960
	ds_read_b128 v[114:117], v244 offset:45056
	s_add_i32 s22, s21, 64
	s_cmp_le_u32 s22, s20
	s_cbranch_scc0 .Lr2u1_Lnear_u1e
.Lr2u1_LBB0_188:
	v_mfma_f32_32x32x16_bf16 v[34:49], v[126:129], v[162:165], v[34:49]
	ds_read_b128 v[126:129], v245 offset:32768
	s_nop 0
	v_exp_f32_e32 v130, v82
	v_exp_f32_e32 v131, v83
	v_add_f32_e32 v132, v1, v130
	v_add_f32_e32 v133, v1, v131
	v_cvt_pk_bf16_f32 v166, v130, v131
	s_waitcnt lgkmcnt(3)
	v_mfma_f32_32x32x16_bf16 v[50:65], v[122:125], v[162:165], v[50:65]
	ds_read_b128 v[122:125], v245 offset:36864
	v_exp_f32_e32 v134, v84
	v_exp_f32_e32 v135, v85
	s_add_i32 s22, s23, 2
	v_add_f32_e32 v130, v132, v134
	v_add_f32_e32 v131, v133, v135
	v_cvt_pk_bf16_f32 v167, v134, v135
	s_add_i32 m0, s11, 0x4000
	s_cmp_ge_u32 s22, s17
	s_cbranch_scc1 .Lr2u1_LBB0_190
	global_load_lds_dwordx4 v214, s[80:81]
	s_add_i32 m0, s11, 0x6000
	s_nop 0
	global_load_lds_dwordx4 v214, s[62:63]

.Lr2u1_LBB0_192:
	s_waitcnt lgkmcnt(2)
	v_mfma_f32_32x32x16_bf16 v[18:33], v[118:121], v[170:173], v[18:33]
	ds_read_b128 v[118:121], v246 offset:40960
	v_exp_f32_e32 v133, v94
	v_exp_f32_e32 v134, v95
	v_add_f32_e32 v131, v131, v133
	v_add_f32_e32 v132, v132, v134
	v_cvt_pk_bf16_f32 v176, v133, v134
	v_mfma_f32_32x32x16_bf16 v[2:17], v[114:117], v[170:173], v[2:17]
	ds_read_b128 v[114:117], v246 offset:45056
	v_exp_f32_e32 v130, v96
	v_exp_f32_e32 v133, v97
	v_add_f32_e32 v131, v131, v130
	v_add_f32_e32 v132, v132, v133
	v_cvt_pk_bf16_f32 v177, v130, v133
	s_waitcnt lgkmcnt(2)
	v_mfma_f32_32x32x16_bf16 v[34:49], v[126:129], v[178:181], v[34:49]
	ds_read_b128 v[126:129], v247 offset:32768
	v_exp_f32_e32 v133, v98
	v_exp_f32_e32 v134, v99
	v_add_f32_e32 v131, v131, v133
	v_add_f32_e32 v132, v132, v134
	v_cvt_pk_bf16_f32 v182, v133, v134
	v_mfma_f32_32x32x16_bf16 v[50:65], v[122:125], v[178:181], v[50:65]
	v_exp_f32_e32 v133, v100
	v_exp_f32_e32 v134, v101
	ds_read_b128 v[122:125], v247 offset:36864
	v_add_f32_e32 v131, v131, v133
	v_add_f32_e32 v132, v132, v134
	v_cvt_pk_bf16_f32 v183, v133, v134
	s_add_i32 m0, s11, 0xc000
	s_cmp_eq_u64 s[88:89], 0
	s_cbranch_scc1 .Lr2u1_LBB0_194
	global_load_lds_dwordx4 v216, s[96:97]
	s_add_i32 m0, s11, 0xe000
	s_nop 0
	global_load_lds_dwordx4 v216, s[58:59]

.Lr2u1_LBB0_225:
	ds_read_b128 v[126:129], v244 offset:49152
	s_waitcnt lgkmcnt(1)
	v_mfma_f32_32x32x16_bf16 v[82:97], v[98:101], v[146:149], v[66:81]
	ds_read_b128 v[122:125], v240 offset:8192
	v_mfma_f32_32x32x16_bf16 v[98:113], v[114:117], v[146:149], v[66:81]
	ds_read_b128 v[114:117], v241
	v_mfma_f32_32x32x16_bf16 v[82:97], v[118:121], v[150:153], v[82:97]
	ds_read_b128 v[118:121], v241 offset:8192
	s_waitcnt lgkmcnt(0)
	v_mfma_f32_32x32x16_bf16 v[98:113], v[122:125], v[150:153], v[98:113]
	ds_read_b128 v[122:125], v243
	v_mfma_f32_32x32x16_bf16 v[82:97], v[114:117], v[154:157], v[82:97]
	ds_read_b128 v[114:117], v243 offset:8192
	v_mfma_f32_32x32x16_bf16 v[98:113], v[118:121], v[154:157], v[98:113]
	s_waitcnt lgkmcnt(0)
	v_mfma_f32_32x32x16_bf16 v[82:97], v[122:125], v[158:161], v[82:97]
	v_mfma_f32_32x32x16_bf16 v[98:113], v[114:117], v[158:161], v[98:113]
	s_nop 0
	ds_read_b128 v[122:125], v244 offset:53248
	ds_read_b128 v[118:121], v244 offset:57344
	ds_read_b128 v[114:117], v244 offset:61440
	s_add_i32 s26, s21, 0x80
	s_cmp_le_u32 s26, s20
	s_cbranch_scc0 .Lr2u1_Lnear_u1o
.Lr2u1_LBB0_228:
	v_mfma_f32_32x32x16_bf16 v[34:49], v[126:129], v[166:169], v[34:49]
	ds_read_b128 v[126:129], v245 offset:49152
	s_nop 0
	v_exp_f32_e32 v130, v82
	v_exp_f32_e32 v131, v83
	v_add_f32_e32 v132, v1, v130
	v_add_f32_e32 v133, v1, v131
	v_cvt_pk_bf16_f32 v162, v130, v131
	s_waitcnt lgkmcnt(3)
	v_mfma_f32_32x32x16_bf16 v[50:65], v[122:125], v[166:169], v[50:65]
	ds_read_b128 v[122:125], v245 offset:53248
	v_exp_f32_e32 v130, v84
	v_exp_f32_e32 v131, v85
	s_add_i32 s23, s23, 3
	v_add_f32_e32 v132, v132, v130
	v_add_f32_e32 v133, v133, v131
	v_cvt_pk_bf16_f32 v163, v130, v131
	s_add_i32 m0, s11, 0x8000
	s_cmp_gt_u32 s23, s16
	s_cbranch_scc1 .Lr2u1_LBB0_230
	global_load_lds_dwordx4 v214, s[50:51]
	s_add_i32 m0, s11, 0xa000
	s_nop 0
	global_load_lds_dwordx4 v214, s[4:5]

.Lr2u1_LBB0_232:
	s_waitcnt lgkmcnt(2)
	v_mfma_f32_32x32x16_bf16 v[18:33], v[118:121], v[174:177], v[18:33]
	ds_read_b128 v[118:121], v246 offset:57344
	v_exp_f32_e32 v130, v94
	v_exp_f32_e32 v131, v95
	v_add_f32_e32 v133, v133, v130
	v_add_f32_e32 v134, v134, v131
	v_cvt_pk_bf16_f32 v172, v130, v131
	v_mfma_f32_32x32x16_bf16 v[2:17], v[114:117], v[174:177], v[2:17]
	ds_read_b128 v[114:117], v246 offset:61440
	v_exp_f32_e32 v130, v96
	v_exp_f32_e32 v131, v97
	v_add_f32_e32 v133, v133, v130
	v_add_f32_e32 v134, v134, v131
	v_cvt_pk_bf16_f32 v173, v130, v131
	s_waitcnt lgkmcnt(2)
	v_mfma_f32_32x32x16_bf16 v[34:49], v[126:129], v[182:185], v[34:49]
	ds_read_b128 v[126:129], v247 offset:49152
	v_exp_f32_e32 v130, v98
	v_exp_f32_e32 v131, v99
	v_add_f32_e32 v133, v133, v130
	v_add_f32_e32 v134, v134, v131
	v_cvt_pk_bf16_f32 v178, v130, v131
	v_mfma_f32_32x32x16_bf16 v[50:65], v[122:125], v[182:185], v[50:65]
	v_exp_f32_e32 v130, v100
	v_exp_f32_e32 v131, v101
	ds_read_b128 v[122:125], v247 offset:53248
	v_add_f32_e32 v133, v133, v130
	v_add_f32_e32 v134, v134, v131
	v_cvt_pk_bf16_f32 v179, v130, v131
	s_add_i32 m0, s11, 0x10000
	s_cmp_eq_u64 s[88:89], 0
	s_cbranch_scc1 .Lr2u1_LBB0_234
	global_load_lds_dwordx4 v216, s[0:1]
	s_add_i32 m0, s11, 0x12000
	s_nop 0
	global_load_lds_dwordx4 v216, s[52:53]

.Lr2u1_Lpvo_u1e:
	s_mov_b32 s54, 0xffffc000
	v_add_u32_e32 v249, s54, v244
	v_add_u32_e32 v212, s54, v245
	s_mov_b64 s[26:27], -1
	ds_read_b128 v[98:101], v249 offset:49152
	ds_read_b128 v[114:117], v249 offset:53248
	ds_read_b128 v[130:133], v249 offset:57344
	ds_read_b128 v[194:197], v249 offset:61440
	s_waitcnt lgkmcnt(0)
	v_mfma_f32_32x32x16_bf16 v[82:97], v[98:101], v[162:165], v[34:49]
	ds_read_b128 v[206:209], v212 offset:49152
	v_mfma_f32_32x32x16_bf16 v[98:113], v[114:117], v[162:165], v[50:65]
	ds_read_b128 v[198:201], v212 offset:53248
	s_add_i32 s22, s23, 2
	s_cmp_lt_u32 s22, s17
	s_cselect_b64 s[26:27], -1, 0
	s_cmp_ge_u32 s22, s17
	s_cbranch_scc1 .Lr2u1_LBB0_178
	s_mov_b32 s40, 0x4000
	s_add_i32 m0, s11, s40
	s_nop 0
	global_load_lds_dwordx4 v214, s[80:81]

.Lr2u1_Lpvo_u1o:
	s_mov_b32 s54, 0x0
	v_add_u32_e32 v249, s54, v244
	v_add_u32_e32 v212, s54, v245
	s_mov_b64 s[26:27], -1
	ds_read_b128 v[98:101], v249 offset:49152
	ds_read_b128 v[114:117], v249 offset:53248
	ds_read_b128 v[130:133], v249 offset:57344
	ds_read_b128 v[194:197], v249 offset:61440
	s_waitcnt lgkmcnt(0)
	v_mfma_f32_32x32x16_bf16 v[82:97], v[98:101], v[166:169], v[34:49]
	ds_read_b128 v[206:209], v212 offset:49152
	v_mfma_f32_32x32x16_bf16 v[98:113], v[114:117], v[166:169], v[50:65]
	ds_read_b128 v[198:201], v212 offset:53248
	s_add_i32 s40, s23, 3
	s_cmp_le_u32 s40, s16
	s_cselect_b64 s[26:27], -1, 0
	s_cmp_gt_u32 s40, s16
	s_cbranch_scc1 .Lr2u1_LBB0_218
	s_mov_b32 s40, 0x8000
	s_add_i32 m0, s11, s40
	s_nop 0
	global_load_lds_dwordx4 v214, s[50:51]

.LBB0_277:
	s_cmp_ge_u32 s22, s19
	s_cbranch_scc1 .Lslow_u2e
.LBB0_288:
	ds_read_b128 v[126:129], v245 offset:16384
	s_waitcnt lgkmcnt(1)
	v_mfma_f32_32x32x16_bf16 v[82:97], v[98:101], v[146:149], v[66:81]
	ds_read_b128 v[122:125], v240 offset:24576
	v_mfma_f32_32x32x16_bf16 v[98:113], v[114:117], v[146:149], v[66:81]
	ds_read_b128 v[114:117], v241 offset:16384
	v_mfma_f32_32x32x16_bf16 v[82:97], v[118:121], v[150:153], v[82:97]
	ds_read_b128 v[118:121], v241 offset:24576
	s_waitcnt lgkmcnt(0)
	v_mfma_f32_32x32x16_bf16 v[98:113], v[122:125], v[150:153], v[98:113]
	ds_read_b128 v[122:125], v242 offset:16384
	v_mfma_f32_32x32x16_bf16 v[82:97], v[114:117], v[154:157], v[82:97]
	ds_read_b128 v[114:117], v242 offset:24576
	v_mfma_f32_32x32x16_bf16 v[98:113], v[118:121], v[154:157], v[98:113]
	s_waitcnt lgkmcnt(0)
	v_mfma_f32_32x32x16_bf16 v[82:97], v[122:125], v[158:161], v[82:97]
	v_mfma_f32_32x32x16_bf16 v[98:113], v[114:117], v[158:161], v[98:113]
	s_nop 0
	ds_read_b128 v[122:125], v245 offset:20480
	ds_read_b128 v[118:121], v245 offset:24576
	ds_read_b128 v[114:117], v245 offset:28672
	s_cmp_le_u32 s20, s16
	s_cbranch_scc0 .Lnear_u2e
.LBB0_291:
	v_mfma_f32_32x32x16_bf16 v[50:65], v[126:129], v[162:165], v[50:65]
	ds_read_b128 v[126:129], v246 offset:16384
	s_nop 1
	v_exp_f32_e32 v130, v82
	v_exp_f32_e32 v131, v83
	v_add_f32_e32 v132, v1, v130
	v_add_f32_e32 v133, v1, v131
	v_cvt_pk_bf16_f32 v166, v130, v131
	s_waitcnt lgkmcnt(3)
	v_mfma_f32_32x32x16_bf16 v[34:49], v[122:125], v[162:165], v[34:49]
	ds_read_b128 v[122:125], v246 offset:20480
	v_exp_f32_e32 v134, v84
	v_exp_f32_e32 v135, v85
	s_add_i32 s21, s22, 2
	v_add_f32_e32 v130, v132, v134
	v_add_f32_e32 v131, v133, v135
	v_cvt_pk_bf16_f32 v167, v134, v135
	s_mov_b32 m0, s10
	s_cmp_ge_u32 s21, s18
	s_cbranch_scc1 .LBB0_293
	global_load_lds_dwordx4 v214, s[80:81]
	s_add_i32 m0, s10, 0x2000
	s_nop 0
	global_load_lds_dwordx4 v214, s[62:63]

.LBB0_295:
	s_waitcnt lgkmcnt(2)
	v_mfma_f32_32x32x16_bf16 v[18:33], v[118:121], v[170:173], v[18:33]
	ds_read_b128 v[118:121], v247 offset:24576
	v_exp_f32_e32 v132, v94
	v_exp_f32_e32 v133, v95
	v_add_f32_e32 v130, v130, v132
	v_add_f32_e32 v131, v131, v133
	v_cvt_pk_bf16_f32 v176, v132, v133
	v_mfma_f32_32x32x16_bf16 v[2:17], v[114:117], v[170:173], v[2:17]
	ds_read_b128 v[114:117], v247 offset:28672
	v_exp_f32_e32 v0, v96
	v_exp_f32_e32 v132, v97
	v_add_f32_e32 v130, v130, v0
	v_add_f32_e32 v131, v131, v132
	v_cvt_pk_bf16_f32 v177, v0, v132
	s_waitcnt lgkmcnt(2)
	v_mfma_f32_32x32x16_bf16 v[50:65], v[126:129], v[178:181], v[50:65]
	ds_read_b128 v[126:129], v248 offset:16384
	v_exp_f32_e32 v132, v98
	v_exp_f32_e32 v133, v99
	v_add_f32_e32 v130, v130, v132
	v_add_f32_e32 v131, v131, v133
	v_cvt_pk_bf16_f32 v182, v132, v133
	v_mfma_f32_32x32x16_bf16 v[34:49], v[122:125], v[178:181], v[34:49]
	v_exp_f32_e32 v132, v100
	v_exp_f32_e32 v133, v101
	ds_read_b128 v[122:125], v248 offset:20480
	v_add_f32_e32 v130, v130, v132
	v_add_f32_e32 v131, v131, v133
	v_cvt_pk_bf16_f32 v183, v132, v133
	s_add_i32 m0, s10, 0x14000
	s_cmp_eq_u64 s[44:45], 0
	s_cbranch_scc1 .LBB0_297
	global_load_lds_dwordx4 v216, s[96:97]
	s_add_i32 m0, s10, 0x16000
	s_nop 0
	global_load_lds_dwordx4 v216, s[58:59]

.LBB0_317:
	s_add_i32 s37, s22, 1
	s_cmp_ge_u32 s37, s19
	s_cbranch_scc1 .Lslow_u2o
.LBB0_328:
	ds_read_b128 v[126:129], v245 offset:32768
	s_waitcnt lgkmcnt(1)
	v_mfma_f32_32x32x16_bf16 v[82:97], v[98:101], v[146:149], v[66:81]
	ds_read_b128 v[122:125], v240 offset:40960
	v_mfma_f32_32x32x16_bf16 v[98:113], v[114:117], v[146:149], v[66:81]
	ds_read_b128 v[114:117], v241 offset:32768
	v_mfma_f32_32x32x16_bf16 v[82:97], v[118:121], v[150:153], v[82:97]
	ds_read_b128 v[118:121], v241 offset:40960
	s_waitcnt lgkmcnt(0)
	v_mfma_f32_32x32x16_bf16 v[98:113], v[122:125], v[150:153], v[98:113]
	ds_read_b128 v[122:125], v242 offset:32768
	v_mfma_f32_32x32x16_bf16 v[82:97], v[114:117], v[154:157], v[82:97]
	ds_read_b128 v[114:117], v242 offset:40960
	v_mfma_f32_32x32x16_bf16 v[98:113], v[118:121], v[154:157], v[98:113]
	s_waitcnt lgkmcnt(0)
	v_mfma_f32_32x32x16_bf16 v[82:97], v[122:125], v[158:161], v[82:97]
	v_mfma_f32_32x32x16_bf16 v[98:113], v[114:117], v[158:161], v[98:113]
	s_nop 0
	ds_read_b128 v[122:125], v245 offset:36864
	ds_read_b128 v[118:121], v245 offset:40960
	ds_read_b128 v[114:117], v245 offset:45056
	s_add_i32 s26, s20, 64
	s_cmp_le_u32 s26, s16
	s_cbranch_scc0 .Lnear_u2o
.LBB0_331:
	v_mfma_f32_32x32x16_bf16 v[50:65], v[126:129], v[166:169], v[50:65]
	ds_read_b128 v[126:129], v246 offset:32768
	s_nop 0
	v_exp_f32_e32 v130, v82
	v_exp_f32_e32 v131, v83
	v_add_f32_e32 v132, v1, v130
	v_add_f32_e32 v133, v1, v131
	v_cvt_pk_bf16_f32 v162, v130, v131
	s_waitcnt lgkmcnt(3)
	v_mfma_f32_32x32x16_bf16 v[34:49], v[122:125], v[166:169], v[34:49]
	ds_read_b128 v[122:125], v246 offset:36864
	v_exp_f32_e32 v130, v84
	v_exp_f32_e32 v131, v85
	s_add_i32 s22, s22, 3
	v_add_f32_e32 v132, v132, v130
	v_add_f32_e32 v133, v133, v131
	v_cvt_pk_bf16_f32 v163, v130, v131
	s_add_i32 m0, s10, 0x4000
	s_cmp_gt_u32 s22, s17
	s_cbranch_scc1 .LBB0_333
	global_load_lds_dwordx4 v214, s[50:51]
	s_add_i32 m0, s10, 0x6000
	s_nop 0
	global_load_lds_dwordx4 v214, s[4:5]

.LBB0_335:
	s_waitcnt lgkmcnt(2)
	v_mfma_f32_32x32x16_bf16 v[18:33], v[118:121], v[174:177], v[18:33]
	ds_read_b128 v[118:121], v247 offset:40960
	v_exp_f32_e32 v130, v94
	v_exp_f32_e32 v131, v95
	v_add_f32_e32 v132, v132, v130
	v_add_f32_e32 v133, v133, v131
	v_cvt_pk_bf16_f32 v172, v130, v131
	v_mfma_f32_32x32x16_bf16 v[2:17], v[114:117], v[174:177], v[2:17]
	ds_read_b128 v[114:117], v247 offset:45056
	v_exp_f32_e32 v0, v96
	v_exp_f32_e32 v130, v97
	v_add_f32_e32 v131, v132, v0
	v_add_f32_e32 v132, v133, v130
	v_cvt_pk_bf16_f32 v173, v0, v130
	s_waitcnt lgkmcnt(2)
	v_mfma_f32_32x32x16_bf16 v[50:65], v[126:129], v[182:185], v[50:65]
	ds_read_b128 v[126:129], v248 offset:32768
	v_exp_f32_e32 v130, v98
	v_exp_f32_e32 v133, v99
	v_add_f32_e32 v131, v131, v130
	v_add_f32_e32 v134, v132, v133
	v_cvt_pk_bf16_f32 v178, v130, v133
	v_mfma_f32_32x32x16_bf16 v[34:49], v[122:125], v[182:185], v[34:49]
	v_exp_f32_e32 v130, v100
	v_exp_f32_e32 v135, v101
	ds_read_b128 v[122:125], v248 offset:36864
	v_add_f32_e32 v132, v131, v130
	v_add_f32_e32 v133, v134, v135
	v_cvt_pk_bf16_f32 v179, v130, v135
	s_add_i32 m0, s10, 0xc000
	s_cmp_eq_u64 s[44:45], 0
	s_cbranch_scc1 .LBB0_337
	global_load_lds_dwordx4 v216, s[0:1]
	s_add_i32 m0, s10, 0xe000
	s_nop 0
	global_load_lds_dwordx4 v216, s[52:53]

.Lpvo_u2e:
	s_mov_b32 s36, 0xffff8000
	v_add_u32_e32 v212, s36, v245
	v_add_u32_e32 v0, s36, v246
	s_mov_b64 s[26:27], -1
	ds_read_b128 v[98:101], v212 offset:49152
	ds_read_b128 v[114:117], v212 offset:53248
	ds_read_b128 v[130:133], v212 offset:57344
	ds_read_b128 v[194:197], v212 offset:61440
	s_waitcnt lgkmcnt(0)
	v_mfma_f32_32x32x16_bf16 v[82:97], v[98:101], v[162:165], v[50:65]
	ds_read_b128 v[206:209], v0 offset:49152
	v_mfma_f32_32x32x16_bf16 v[98:113], v[114:117], v[162:165], v[34:49]
	ds_read_b128 v[198:201], v0 offset:53248
	s_add_i32 s21, s22, 2
	s_cmp_lt_u32 s21, s18
	s_cselect_b64 s[26:27], -1, 0
	s_cmp_ge_u32 s21, s18
	s_cbranch_scc1 .LBB0_281
	s_mov_b32 s37, 0x0
	s_add_i32 m0, s10, s37
	s_nop 0
	global_load_lds_dwordx4 v214, s[80:81]

.Lpvo_u2o:
	s_mov_b32 s36, 0xffffc000
	v_add_u32_e32 v212, s36, v245
	v_add_u32_e32 v0, s36, v246
	s_mov_b64 s[26:27], -1
	ds_read_b128 v[98:101], v212 offset:49152
	ds_read_b128 v[114:117], v212 offset:53248
	ds_read_b128 v[130:133], v212 offset:57344
	ds_read_b128 v[194:197], v212 offset:61440
	s_waitcnt lgkmcnt(0)
	v_mfma_f32_32x32x16_bf16 v[82:97], v[98:101], v[166:169], v[50:65]
	ds_read_b128 v[206:209], v0 offset:49152
	v_mfma_f32_32x32x16_bf16 v[98:113], v[114:117], v[166:169], v[34:49]
	ds_read_b128 v[198:201], v0 offset:53248
	s_add_i32 s37, s22, 3
	s_cmp_le_u32 s37, s17
	s_cselect_b64 s[26:27], -1, 0
	s_cmp_gt_u32 s37, s17
	s_cbranch_scc1 .LBB0_321
	s_mov_b32 s37, 0x4000
	s_add_i32 m0, s10, s37
	s_nop 0
	global_load_lds_dwordx4 v214, s[50:51]

.Lr1u2_LBB0_288:
	ds_read_b128 v[126:129], v245 offset:49152
	s_waitcnt lgkmcnt(1)
	v_mfma_f32_32x32x16_bf16 v[82:97], v[98:101], v[146:149], v[66:81]
	ds_read_b128 v[122:125], v240 offset:8192
	v_mfma_f32_32x32x16_bf16 v[98:113], v[114:117], v[146:149], v[66:81]
	ds_read_b128 v[114:117], v241
	v_mfma_f32_32x32x16_bf16 v[82:97], v[118:121], v[150:153], v[82:97]
	ds_read_b128 v[118:121], v241 offset:8192
	s_waitcnt lgkmcnt(0)
	v_mfma_f32_32x32x16_bf16 v[98:113], v[122:125], v[150:153], v[98:113]
	ds_read_b128 v[122:125], v242
	v_mfma_f32_32x32x16_bf16 v[82:97], v[114:117], v[154:157], v[82:97]
	ds_read_b128 v[114:117], v242 offset:8192
	v_mfma_f32_32x32x16_bf16 v[98:113], v[118:121], v[154:157], v[98:113]
	s_waitcnt lgkmcnt(0)
	v_mfma_f32_32x32x16_bf16 v[82:97], v[122:125], v[158:161], v[82:97]
	v_mfma_f32_32x32x16_bf16 v[98:113], v[114:117], v[158:161], v[98:113]
	s_nop 0
	ds_read_b128 v[122:125], v245 offset:53248
	ds_read_b128 v[118:121], v245 offset:57344
	ds_read_b128 v[114:117], v245 offset:61440
	s_cmp_le_u32 s20, s16
	s_cbranch_scc0 .Lr1u2_Lnear_u2e
.Lr1u2_LBB0_291:
	v_mfma_f32_32x32x16_bf16 v[50:65], v[126:129], v[162:165], v[50:65]
	ds_read_b128 v[126:129], v246 offset:49152
	s_nop 1
	v_exp_f32_e32 v130, v82
	v_exp_f32_e32 v131, v83
	v_add_f32_e32 v132, v1, v130
	v_add_f32_e32 v133, v1, v131
	v_cvt_pk_bf16_f32 v166, v130, v131
	s_waitcnt lgkmcnt(3)
	v_mfma_f32_32x32x16_bf16 v[34:49], v[122:125], v[162:165], v[34:49]
	ds_read_b128 v[122:125], v246 offset:53248
	v_exp_f32_e32 v134, v84
	v_exp_f32_e32 v135, v85
	s_add_i32 s21, s22, 2
	v_add_f32_e32 v130, v132, v134
	v_add_f32_e32 v131, v133, v135
	v_cvt_pk_bf16_f32 v167, v134, v135
	s_add_i32 m0, s10, 0x8000
	s_cmp_ge_u32 s21, s18
	s_cbranch_scc1 .Lr1u2_LBB0_293
	global_load_lds_dwordx4 v214, s[80:81]
	s_add_i32 m0, s10, 0xa000
	s_nop 0
	global_load_lds_dwordx4 v214, s[62:63]

.Lr1u2_LBB0_295:
	s_waitcnt lgkmcnt(2)
	v_mfma_f32_32x32x16_bf16 v[18:33], v[118:121], v[170:173], v[18:33]
	ds_read_b128 v[118:121], v247 offset:57344
	v_exp_f32_e32 v132, v94
	v_exp_f32_e32 v133, v95
	v_add_f32_e32 v130, v130, v132
	v_add_f32_e32 v131, v131, v133
	v_cvt_pk_bf16_f32 v176, v132, v133
	v_mfma_f32_32x32x16_bf16 v[2:17], v[114:117], v[170:173], v[2:17]
	ds_read_b128 v[114:117], v247 offset:61440
	v_exp_f32_e32 v0, v96
	v_exp_f32_e32 v132, v97
	v_add_f32_e32 v130, v130, v0
	v_add_f32_e32 v131, v131, v132
	v_cvt_pk_bf16_f32 v177, v0, v132
	s_waitcnt lgkmcnt(2)
	v_mfma_f32_32x32x16_bf16 v[50:65], v[126:129], v[178:181], v[50:65]
	ds_read_b128 v[126:129], v248 offset:49152
	v_exp_f32_e32 v132, v98
	v_exp_f32_e32 v133, v99
	v_add_f32_e32 v130, v130, v132
	v_add_f32_e32 v131, v131, v133
	v_cvt_pk_bf16_f32 v182, v132, v133
	v_mfma_f32_32x32x16_bf16 v[34:49], v[122:125], v[178:181], v[34:49]
	v_exp_f32_e32 v132, v100
	v_exp_f32_e32 v133, v101
	ds_read_b128 v[122:125], v248 offset:53248
	v_add_f32_e32 v130, v130, v132
	v_add_f32_e32 v131, v131, v133
	v_cvt_pk_bf16_f32 v183, v132, v133
	s_add_i32 m0, s10, 0x10000
	s_cmp_eq_u64 s[44:45], 0
	s_cbranch_scc1 .Lr1u2_LBB0_297
	global_load_lds_dwordx4 v216, s[96:97]
	s_add_i32 m0, s10, 0x12000
	s_nop 0
	global_load_lds_dwordx4 v216, s[58:59]

.Lr1u2_LBB0_328:
	ds_read_b128 v[126:129], v245 offset:16384
	s_waitcnt lgkmcnt(1)
	v_mfma_f32_32x32x16_bf16 v[82:97], v[98:101], v[146:149], v[66:81]
	ds_read_b128 v[122:125], v240 offset:24576
	v_mfma_f32_32x32x16_bf16 v[98:113], v[114:117], v[146:149], v[66:81]
	ds_read_b128 v[114:117], v241 offset:16384
	v_mfma_f32_32x32x16_bf16 v[82:97], v[118:121], v[150:153], v[82:97]
	ds_read_b128 v[118:121], v241 offset:24576
	s_waitcnt lgkmcnt(0)
	v_mfma_f32_32x32x16_bf16 v[98:113], v[122:125], v[150:153], v[98:113]
	ds_read_b128 v[122:125], v242 offset:16384
	v_mfma_f32_32x32x16_bf16 v[82:97], v[114:117], v[154:157], v[82:97]
	ds_read_b128 v[114:117], v242 offset:24576
	v_mfma_f32_32x32x16_bf16 v[98:113], v[118:121], v[154:157], v[98:113]
	s_waitcnt lgkmcnt(0)
	v_mfma_f32_32x32x16_bf16 v[82:97], v[122:125], v[158:161], v[82:97]
	v_mfma_f32_32x32x16_bf16 v[98:113], v[114:117], v[158:161], v[98:113]
	s_nop 0
	ds_read_b128 v[122:125], v245 offset:20480
	ds_read_b128 v[118:121], v245 offset:24576
	ds_read_b128 v[114:117], v245 offset:28672
	s_add_i32 s26, s20, 64
	s_cmp_le_u32 s26, s16
	s_cbranch_scc0 .Lr1u2_Lnear_u2o
.Lr1u2_LBB0_331:
	v_mfma_f32_32x32x16_bf16 v[50:65], v[126:129], v[166:169], v[50:65]
	ds_read_b128 v[126:129], v246 offset:16384
	s_nop 0
	v_exp_f32_e32 v130, v82
	v_exp_f32_e32 v131, v83
	v_add_f32_e32 v132, v1, v130
	v_add_f32_e32 v133, v1, v131
	v_cvt_pk_bf16_f32 v162, v130, v131
	s_waitcnt lgkmcnt(3)
	v_mfma_f32_32x32x16_bf16 v[34:49], v[122:125], v[166:169], v[34:49]
	ds_read_b128 v[122:125], v246 offset:20480
	v_exp_f32_e32 v130, v84
	v_exp_f32_e32 v131, v85
	s_add_i32 s22, s22, 3
	v_add_f32_e32 v132, v132, v130
	v_add_f32_e32 v133, v133, v131
	v_cvt_pk_bf16_f32 v163, v130, v131
	s_mov_b32 m0, s10
	s_cmp_gt_u32 s22, s17
	s_cbranch_scc1 .Lr1u2_LBB0_333
	global_load_lds_dwordx4 v214, s[50:51]
	s_add_i32 m0, s10, 0x2000
	s_nop 0
	global_load_lds_dwordx4 v214, s[4:5]

.Lr1u2_LBB0_335:
	s_waitcnt lgkmcnt(2)
	v_mfma_f32_32x32x16_bf16 v[18:33], v[118:121], v[174:177], v[18:33]
	ds_read_b128 v[118:121], v247 offset:24576
	v_exp_f32_e32 v130, v94
	v_exp_f32_e32 v131, v95
	v_add_f32_e32 v132, v132, v130
	v_add_f32_e32 v133, v133, v131
	v_cvt_pk_bf16_f32 v172, v130, v131
	v_mfma_f32_32x32x16_bf16 v[2:17], v[114:117], v[174:177], v[2:17]
	ds_read_b128 v[114:117], v247 offset:28672
	v_exp_f32_e32 v0, v96
	v_exp_f32_e32 v130, v97
	v_add_f32_e32 v131, v132, v0
	v_add_f32_e32 v132, v133, v130
	v_cvt_pk_bf16_f32 v173, v0, v130
	s_waitcnt lgkmcnt(2)
	v_mfma_f32_32x32x16_bf16 v[50:65], v[126:129], v[182:185], v[50:65]
	ds_read_b128 v[126:129], v248 offset:16384
	v_exp_f32_e32 v130, v98
	v_exp_f32_e32 v133, v99
	v_add_f32_e32 v131, v131, v130
	v_add_f32_e32 v134, v132, v133
	v_cvt_pk_bf16_f32 v178, v130, v133
	v_mfma_f32_32x32x16_bf16 v[34:49], v[122:125], v[182:185], v[34:49]
	v_exp_f32_e32 v130, v100
	v_exp_f32_e32 v135, v101
	ds_read_b128 v[122:125], v248 offset:20480
	v_add_f32_e32 v132, v131, v130
	v_add_f32_e32 v133, v134, v135
	v_cvt_pk_bf16_f32 v179, v130, v135
	s_add_i32 m0, s10, 0x14000
	s_cmp_eq_u64 s[44:45], 0
	s_cbranch_scc1 .Lr1u2_LBB0_337
	global_load_lds_dwordx4 v216, s[0:1]
	s_add_i32 m0, s10, 0x16000
	s_nop 0
	global_load_lds_dwordx4 v216, s[52:53]

.Lr1u2_Lpvo_u2e:
	s_mov_b32 s36, 0x0
	v_add_u32_e32 v212, s36, v245
	v_add_u32_e32 v0, s36, v246
	s_mov_b64 s[26:27], -1
	ds_read_b128 v[98:101], v212 offset:49152
	ds_read_b128 v[114:117], v212 offset:53248
	ds_read_b128 v[130:133], v212 offset:57344
	ds_read_b128 v[194:197], v212 offset:61440
	s_waitcnt lgkmcnt(0)
	v_mfma_f32_32x32x16_bf16 v[82:97], v[98:101], v[162:165], v[50:65]
	ds_read_b128 v[206:209], v0 offset:49152
	v_mfma_f32_32x32x16_bf16 v[98:113], v[114:117], v[162:165], v[34:49]
	ds_read_b128 v[198:201], v0 offset:53248
	s_add_i32 s21, s22, 2
	s_cmp_lt_u32 s21, s18
	s_cselect_b64 s[26:27], -1, 0
	s_cmp_ge_u32 s21, s18
	s_cbranch_scc1 .Lr1u2_LBB0_281
	s_mov_b32 s37, 0x8000
	s_add_i32 m0, s10, s37
	s_nop 0
	global_load_lds_dwordx4 v214, s[80:81]

.Lr1u2_Lpvo_u2o:
	s_mov_b32 s36, 0xffff8000
	v_add_u32_e32 v212, s36, v245
	v_add_u32_e32 v0, s36, v246
	s_mov_b64 s[26:27], -1
	ds_read_b128 v[98:101], v212 offset:49152
	ds_read_b128 v[114:117], v212 offset:53248
	ds_read_b128 v[130:133], v212 offset:57344
	ds_read_b128 v[194:197], v212 offset:61440
	s_waitcnt lgkmcnt(0)
	v_mfma_f32_32x32x16_bf16 v[82:97], v[98:101], v[166:169], v[50:65]
	ds_read_b128 v[206:209], v0 offset:49152
	v_mfma_f32_32x32x16_bf16 v[98:113], v[114:117], v[166:169], v[34:49]
	ds_read_b128 v[198:201], v0 offset:53248
	s_add_i32 s37, s22, 3
	s_cmp_le_u32 s37, s17
	s_cselect_b64 s[26:27], -1, 0
	s_cmp_gt_u32 s37, s17
	s_cbranch_scc1 .Lr1u2_LBB0_321
	s_mov_b32 s37, 0x0
	s_add_i32 m0, s10, s37
	s_nop 0
	global_load_lds_dwordx4 v214, s[50:51]

.Lr2u2_LBB0_288:
	ds_read_b128 v[126:129], v245 offset:32768
	s_waitcnt lgkmcnt(1)
	v_mfma_f32_32x32x16_bf16 v[82:97], v[98:101], v[146:149], v[66:81]
	ds_read_b128 v[122:125], v240 offset:40960
	v_mfma_f32_32x32x16_bf16 v[98:113], v[114:117], v[146:149], v[66:81]
	ds_read_b128 v[114:117], v241 offset:32768
	v_mfma_f32_32x32x16_bf16 v[82:97], v[118:121], v[150:153], v[82:97]
	ds_read_b128 v[118:121], v241 offset:40960
	s_waitcnt lgkmcnt(0)
	v_mfma_f32_32x32x16_bf16 v[98:113], v[122:125], v[150:153], v[98:113]
	ds_read_b128 v[122:125], v242 offset:32768
	v_mfma_f32_32x32x16_bf16 v[82:97], v[114:117], v[154:157], v[82:97]
	ds_read_b128 v[114:117], v242 offset:40960
	v_mfma_f32_32x32x16_bf16 v[98:113], v[118:121], v[154:157], v[98:113]
	s_waitcnt lgkmcnt(0)
	v_mfma_f32_32x32x16_bf16 v[82:97], v[122:125], v[158:161], v[82:97]
	v_mfma_f32_32x32x16_bf16 v[98:113], v[114:117], v[158:161], v[98:113]
	s_nop 0
	ds_read_b128 v[122:125], v245 offset:36864
	ds_read_b128 v[118:121], v245 offset:40960
	ds_read_b128 v[114:117], v245 offset:45056
	s_cmp_le_u32 s20, s16
	s_cbranch_scc0 .Lr2u2_Lnear_u2e
.Lr2u2_LBB0_291:
	v_mfma_f32_32x32x16_bf16 v[50:65], v[126:129], v[162:165], v[50:65]
	ds_read_b128 v[126:129], v246 offset:32768
	s_nop 1
	v_exp_f32_e32 v130, v82
	v_exp_f32_e32 v131, v83
	v_add_f32_e32 v132, v1, v130
	v_add_f32_e32 v133, v1, v131
	v_cvt_pk_bf16_f32 v166, v130, v131
	s_waitcnt lgkmcnt(3)
	v_mfma_f32_32x32x16_bf16 v[34:49], v[122:125], v[162:165], v[34:49]
	ds_read_b128 v[122:125], v246 offset:36864
	v_exp_f32_e32 v134, v84
	v_exp_f32_e32 v135, v85
	s_add_i32 s21, s22, 2
	v_add_f32_e32 v130, v132, v134
	v_add_f32_e32 v131, v133, v135
	v_cvt_pk_bf16_f32 v167, v134, v135
	s_add_i32 m0, s10, 0x4000
	s_cmp_ge_u32 s21, s18
	s_cbranch_scc1 .Lr2u2_LBB0_293
	global_load_lds_dwordx4 v214, s[80:81]
	s_add_i32 m0, s10, 0x6000
	s_nop 0
	global_load_lds_dwordx4 v214, s[62:63]

.Lr2u2_LBB0_295:
	s_waitcnt lgkmcnt(2)
	v_mfma_f32_32x32x16_bf16 v[18:33], v[118:121], v[170:173], v[18:33]
	ds_read_b128 v[118:121], v247 offset:40960
	v_exp_f32_e32 v132, v94
	v_exp_f32_e32 v133, v95
	v_add_f32_e32 v130, v130, v132
	v_add_f32_e32 v131, v131, v133
	v_cvt_pk_bf16_f32 v176, v132, v133
	v_mfma_f32_32x32x16_bf16 v[2:17], v[114:117], v[170:173], v[2:17]
	ds_read_b128 v[114:117], v247 offset:45056
	v_exp_f32_e32 v0, v96
	v_exp_f32_e32 v132, v97
	v_add_f32_e32 v130, v130, v0
	v_add_f32_e32 v131, v131, v132
	v_cvt_pk_bf16_f32 v177, v0, v132
	s_waitcnt lgkmcnt(2)
	v_mfma_f32_32x32x16_bf16 v[50:65], v[126:129], v[178:181], v[50:65]
	ds_read_b128 v[126:129], v248 offset:32768
	v_exp_f32_e32 v132, v98
	v_exp_f32_e32 v133, v99
	v_add_f32_e32 v130, v130, v132
	v_add_f32_e32 v131, v131, v133
	v_cvt_pk_bf16_f32 v182, v132, v133
	v_mfma_f32_32x32x16_bf16 v[34:49], v[122:125], v[178:181], v[34:49]
	v_exp_f32_e32 v132, v100
	v_exp_f32_e32 v133, v101
	ds_read_b128 v[122:125], v248 offset:36864
	v_add_f32_e32 v130, v130, v132
	v_add_f32_e32 v131, v131, v133
	v_cvt_pk_bf16_f32 v183, v132, v133
	s_add_i32 m0, s10, 0xc000
	s_cmp_eq_u64 s[44:45], 0
	s_cbranch_scc1 .Lr2u2_LBB0_297
	global_load_lds_dwordx4 v216, s[96:97]
	s_add_i32 m0, s10, 0xe000
	s_nop 0
	global_load_lds_dwordx4 v216, s[58:59]

.Lr2u2_LBB0_328:
	ds_read_b128 v[126:129], v245 offset:49152
	s_waitcnt lgkmcnt(1)
	v_mfma_f32_32x32x16_bf16 v[82:97], v[98:101], v[146:149], v[66:81]
	ds_read_b128 v[122:125], v240 offset:8192
	v_mfma_f32_32x32x16_bf16 v[98:113], v[114:117], v[146:149], v[66:81]
	ds_read_b128 v[114:117], v241
	v_mfma_f32_32x32x16_bf16 v[82:97], v[118:121], v[150:153], v[82:97]
	ds_read_b128 v[118:121], v241 offset:8192
	s_waitcnt lgkmcnt(0)
	v_mfma_f32_32x32x16_bf16 v[98:113], v[122:125], v[150:153], v[98:113]
	ds_read_b128 v[122:125], v242
	v_mfma_f32_32x32x16_bf16 v[82:97], v[114:117], v[154:157], v[82:97]
	ds_read_b128 v[114:117], v242 offset:8192
	v_mfma_f32_32x32x16_bf16 v[98:113], v[118:121], v[154:157], v[98:113]
	s_waitcnt lgkmcnt(0)
	v_mfma_f32_32x32x16_bf16 v[82:97], v[122:125], v[158:161], v[82:97]
	v_mfma_f32_32x32x16_bf16 v[98:113], v[114:117], v[158:161], v[98:113]
	s_nop 0
	ds_read_b128 v[122:125], v245 offset:53248
	ds_read_b128 v[118:121], v245 offset:57344
	ds_read_b128 v[114:117], v245 offset:61440
	s_add_i32 s26, s20, 64
	s_cmp_le_u32 s26, s16
	s_cbranch_scc0 .Lr2u2_Lnear_u2o
.Lr2u2_LBB0_331:
	v_mfma_f32_32x32x16_bf16 v[50:65], v[126:129], v[166:169], v[50:65]
	ds_read_b128 v[126:129], v246 offset:49152
	s_nop 0
	v_exp_f32_e32 v130, v82
	v_exp_f32_e32 v131, v83
	v_add_f32_e32 v132, v1, v130
	v_add_f32_e32 v133, v1, v131
	v_cvt_pk_bf16_f32 v162, v130, v131
	s_waitcnt lgkmcnt(3)
	v_mfma_f32_32x32x16_bf16 v[34:49], v[122:125], v[166:169], v[34:49]
	ds_read_b128 v[122:125], v246 offset:53248
	v_exp_f32_e32 v130, v84
	v_exp_f32_e32 v131, v85
	s_add_i32 s22, s22, 3
	v_add_f32_e32 v132, v132, v130
	v_add_f32_e32 v133, v133, v131
	v_cvt_pk_bf16_f32 v163, v130, v131
	s_add_i32 m0, s10, 0x8000
	s_cmp_gt_u32 s22, s17
	s_cbranch_scc1 .Lr2u2_LBB0_333
	global_load_lds_dwordx4 v214, s[50:51]
	s_add_i32 m0, s10, 0xa000
	s_nop 0
	global_load_lds_dwordx4 v214, s[4:5]

.Lr2u2_LBB0_335:
	s_waitcnt lgkmcnt(2)
	v_mfma_f32_32x32x16_bf16 v[18:33], v[118:121], v[174:177], v[18:33]
	ds_read_b128 v[118:121], v247 offset:57344
	v_exp_f32_e32 v130, v94
	v_exp_f32_e32 v131, v95
	v_add_f32_e32 v132, v132, v130
	v_add_f32_e32 v133, v133, v131
	v_cvt_pk_bf16_f32 v172, v130, v131
	v_mfma_f32_32x32x16_bf16 v[2:17], v[114:117], v[174:177], v[2:17]
	ds_read_b128 v[114:117], v247 offset:61440
	v_exp_f32_e32 v0, v96
	v_exp_f32_e32 v130, v97
	v_add_f32_e32 v131, v132, v0
	v_add_f32_e32 v132, v133, v130
	v_cvt_pk_bf16_f32 v173, v0, v130
	s_waitcnt lgkmcnt(2)
	v_mfma_f32_32x32x16_bf16 v[50:65], v[126:129], v[182:185], v[50:65]
	ds_read_b128 v[126:129], v248 offset:49152
	v_exp_f32_e32 v130, v98
	v_exp_f32_e32 v133, v99
	v_add_f32_e32 v131, v131, v130
	v_add_f32_e32 v134, v132, v133
	v_cvt_pk_bf16_f32 v178, v130, v133
	v_mfma_f32_32x32x16_bf16 v[34:49], v[122:125], v[182:185], v[34:49]
	v_exp_f32_e32 v130, v100
	v_exp_f32_e32 v135, v101
	ds_read_b128 v[122:125], v248 offset:53248
	v_add_f32_e32 v132, v131, v130
	v_add_f32_e32 v133, v134, v135
	v_cvt_pk_bf16_f32 v179, v130, v135
	s_add_i32 m0, s10, 0x10000
	s_cmp_eq_u64 s[44:45], 0
	s_cbranch_scc1 .Lr2u2_LBB0_337
	global_load_lds_dwordx4 v216, s[0:1]
	s_add_i32 m0, s10, 0x12000
	s_nop 0
	global_load_lds_dwordx4 v216, s[52:53]

.Lr2u2_Lpvo_u2e:
	s_mov_b32 s36, 0xffffc000
	v_add_u32_e32 v212, s36, v245
	v_add_u32_e32 v0, s36, v246
	s_mov_b64 s[26:27], -1
	ds_read_b128 v[98:101], v212 offset:49152
	ds_read_b128 v[114:117], v212 offset:53248
	ds_read_b128 v[130:133], v212 offset:57344
	ds_read_b128 v[194:197], v212 offset:61440
	s_waitcnt lgkmcnt(0)
	v_mfma_f32_32x32x16_bf16 v[82:97], v[98:101], v[162:165], v[50:65]
	ds_read_b128 v[206:209], v0 offset:49152
	v_mfma_f32_32x32x16_bf16 v[98:113], v[114:117], v[162:165], v[34:49]
	ds_read_b128 v[198:201], v0 offset:53248
	s_add_i32 s21, s22, 2
	s_cmp_lt_u32 s21, s18
	s_cselect_b64 s[26:27], -1, 0
	s_cmp_ge_u32 s21, s18
	s_cbranch_scc1 .Lr2u2_LBB0_281
	s_mov_b32 s37, 0x4000
	s_add_i32 m0, s10, s37
	s_nop 0
	global_load_lds_dwordx4 v214, s[80:81]

.Lr2u2_Lpvo_u2o:
	s_mov_b32 s36, 0x0
	v_add_u32_e32 v212, s36, v245
	v_add_u32_e32 v0, s36, v246
	s_mov_b64 s[26:27], -1
	ds_read_b128 v[98:101], v212 offset:49152
	ds_read_b128 v[114:117], v212 offset:53248
	ds_read_b128 v[130:133], v212 offset:57344
	ds_read_b128 v[194:197], v212 offset:61440
	s_waitcnt lgkmcnt(0)
	v_mfma_f32_32x32x16_bf16 v[82:97], v[98:101], v[166:169], v[50:65]
	ds_read_b128 v[206:209], v0 offset:49152
	v_mfma_f32_32x32x16_bf16 v[98:113], v[114:117], v[166:169], v[34:49]
	ds_read_b128 v[198:201], v0 offset:53248
	s_add_i32 s37, s22, 3
	s_cmp_le_u32 s37, s17
	s_cselect_b64 s[26:27], -1, 0
	s_cmp_gt_u32 s37, s17
	s_cbranch_scc1 .Lr2u2_LBB0_321
	s_mov_b32 s37, 0x8000
	s_add_i32 m0, s10, s37
	s_nop 0
	global_load_lds_dwordx4 v214, s[50:51]
